# grid barrier: the globally last arriver bumps all XCD generation words itself (one release hop); per-XCD last arrivers wait on their XCD word and no longer forward
# speedup vs baseline: 1.0071x; 1.0071x over previous
; __device__ __forceinline__ unsigned xb_ld(unsigned* p)              { return __hip_atomic_load(p, __ATOMIC_RELAXED, __HIP_MEMORY_SCOPE_AGENT); }
; __device__ __forceinline__ unsigned xb_add(unsigned* p, unsigned v) { return __hip_atomic_fetch_add(p, v, __ATOMIC_RELAXED, __HIP_MEMORY_SCOPE_AGENT); }
; #define XB_SPIN(cond, bar) do { unsigned _sp = 0; while (cond) { __builtin_amdgcn_s_sleep(1); \
;     if ((++_sp & 255u) == 0u) { if (xb_ld(&(bar)[XB_TMO])) break; if (_sp > XB_SPIN_CAP) { atomicAdd(&(bar)[XB_TMO], 1u); break; } } } } while (0)
; __device__ __forceinline__ void xcd_barrier(const XcdBarrier& b) {
;     ...
;         const unsigned old = xb_add(&bar[XB_XSUB(b.x)], 1u);
;         const unsigned gen = old / nloc;
;         if (old + 1u == (gen + 1u) * nloc) {
;             __builtin_amdgcn_fence(__ATOMIC_RELEASE, "agent");
;             asm volatile("s_waitcnt vmcnt(0)" ::: "memory");
;             const unsigned og = xb_add(&bar[XB_TOP], 1u);
;             const unsigned tg = og / nx;
;             if (og + 1u == (tg + 1u) * nx) xb_add(&bar[XB_TOPGEN], 1u);
;             else XB_SPIN(xb_ld(&bar[XB_TOPGEN]) == tg, bar);
;             __builtin_amdgcn_fence(__ATOMIC_ACQUIRE, "agent");
;             xb_add(&bar[XB_XGEN(b.x)], 1u);
;             asm volatile("s_waitcnt vmcnt(0)" ::: "memory");
;         } else {
;             XB_SPIN(xb_ld(&bar[XB_XGEN(b.x)]) == gen, bar);
.LBB0_649:
	s_or_b64 exec, exec, s[8:9]
	s_waitcnt vmcnt(0)
	v_readfirstlane_b32 s6, v2
	v_cvt_f32_u32_e32 v2, v0
	v_sub_u32_e32 v3, 0, v0
	v_add_u32_e32 v1, s6, v1
	v_readlane_b32 s6, v253, 44
	v_rcp_iflag_f32_e32 v2, v2
	v_readlane_b32 s7, v253, 45
	s_mov_b64 s[8:9], -1
	v_mul_f32_e32 v2, 0x4f7ffffe, v2
	v_cvt_u32_f32_e32 v2, v2
	v_mul_lo_u32 v3, v3, v2
	v_mul_hi_u32 v3, v2, v3
	v_add_u32_e32 v2, v2, v3
	v_mul_hi_u32 v2, v1, v2
	v_mul_lo_u32 v3, v2, v0
	v_sub_u32_e32 v3, v1, v3
	v_cmp_ge_u32_e32 vcc, v3, v0
	v_add_u32_e32 v4, 1, v2
	v_add_u32_e32 v1, 1, v1
	v_cndmask_b32_e32 v2, v2, v4, vcc
	v_sub_u32_e32 v4, v3, v0
	v_cndmask_b32_e32 v3, v3, v4, vcc
	v_cmp_ge_u32_e32 vcc, v3, v0
	v_add_u32_e32 v3, 1, v2
	s_nop 0
	v_cndmask_b32_e32 v2, v2, v3, vcc
	v_mul_lo_u32 v3, v0, v2
	v_add_u32_e32 v0, v3, v0
	v_cmp_ne_u32_e32 vcc, v1, v0
	v_mov_b64_e32 v[0:1], s[6:7]
	s_mov_b32 s100, 1
	s_and_saveexec_b64 s[6:7], vcc
	s_cbranch_execz .LBB0_662
	s_mov_b32 s100, 0
	v_readlane_b32 s8, v253, 40
	v_readlane_b32 s9, v253, 41
	s_mov_b64 s[10:11], 0
	s_nop 3
	global_load_dword v0, v183, s[8:9] sc1
	s_waitcnt vmcnt(0)
	v_cmp_eq_u32_e32 vcc, v0, v2
	s_and_saveexec_b64 s[8:9], vcc
	s_cbranch_execz .LBB0_661
	s_mov_b32 s20, 1
	s_branch .LBB0_653

; __device__ __forceinline__ unsigned xb_ld(unsigned* p)              { return __hip_atomic_load(p, __ATOMIC_RELAXED, __HIP_MEMORY_SCOPE_AGENT); }
; __device__ __forceinline__ unsigned xb_add(unsigned* p, unsigned v) { return __hip_atomic_fetch_add(p, v, __ATOMIC_RELAXED, __HIP_MEMORY_SCOPE_AGENT); }
; #define XB_SPIN(cond, bar) do { unsigned _sp = 0; while (cond) { __builtin_amdgcn_s_sleep(1); \
;     if ((++_sp & 255u) == 0u) { if (xb_ld(&(bar)[XB_TMO])) break; if (_sp > XB_SPIN_CAP) { atomicAdd(&(bar)[XB_TMO], 1u); break; } } } } while (0)
; __device__ __forceinline__ void xcd_barrier(const XcdBarrier& b) {
;     ...
;             else XB_SPIN(xb_ld(&bar[XB_TOPGEN]) == tg, bar);
;             __builtin_amdgcn_fence(__ATOMIC_ACQUIRE, "agent");
;             xb_add(&bar[XB_XGEN(b.x)], 1u);
;             asm volatile("s_waitcnt vmcnt(0)" ::: "memory");
;         } else {
;             XB_SPIN(xb_ld(&bar[XB_XGEN(b.x)]) == gen, bar);
.LBB0_655:
	v_readlane_b32 s14, v253, 40
	v_readlane_b32 s15, v253, 41
	s_add_i32 s20, s20, 1
	s_mov_b64 s[16:17], -1
	s_nop 2
	global_load_dword v0, v183, s[14:15] sc1
	s_waitcnt vmcnt(0)
	v_cmp_ne_u32_e32 vcc, v0, v2
	s_orn2_b64 s[14:15], vcc, exec
	s_branch .LBB0_652

; __device__ __forceinline__ unsigned xb_ld(unsigned* p)              { return __hip_atomic_load(p, __ATOMIC_RELAXED, __HIP_MEMORY_SCOPE_AGENT); }
; __device__ __forceinline__ unsigned xb_add(unsigned* p, unsigned v) { return __hip_atomic_fetch_add(p, v, __ATOMIC_RELAXED, __HIP_MEMORY_SCOPE_AGENT); }
; #define XB_SPIN(cond, bar) do { unsigned _sp = 0; while (cond) { __builtin_amdgcn_s_sleep(1); \
;     if ((++_sp & 255u) == 0u) { if (xb_ld(&(bar)[XB_TMO])) break; if (_sp > XB_SPIN_CAP) { atomicAdd(&(bar)[XB_TMO], 1u); break; } } } } while (0)
; __device__ __forceinline__ void xcd_barrier(const XcdBarrier& b) {
;     ...
;             const unsigned og = xb_add(&bar[XB_TOP], 1u);
;             const unsigned tg = og / nx;
;             if (og + 1u == (tg + 1u) * nx) xb_add(&bar[XB_TOPGEN], 1u);
;             else XB_SPIN(xb_ld(&bar[XB_TOPGEN]) == tg, bar);
;             __builtin_amdgcn_fence(__ATOMIC_ACQUIRE, "agent");
;             xb_add(&bar[XB_XGEN(b.x)], 1u);
;             asm volatile("s_waitcnt vmcnt(0)" ::: "memory");
;         } else {
;             XB_SPIN(xb_ld(&bar[XB_XGEN(b.x)]) == gen, bar);
;             __builtin_amdgcn_fence(__ATOMIC_ACQUIRE, "agent");
;             asm volatile("s_waitcnt vmcnt(0)" ::: "memory");
;         }
.LBB0_662:
	s_or_b64 exec, exec, s[6:7]
	s_and_saveexec_b64 s[6:7], s[8:9]
	s_cbranch_execz .LBB0_664
	v_mov_b32_e32 v2, 1
	global_atomic_add v[0:1], v2, off
	s_cmp_eq_u32 s100, 1
	s_cbranch_scc0 .Lxg_skip
	v_readlane_b32 s10, v253, 44
	v_readlane_b32 s11, v253, 45
	s_nop 0
	s_sub_u32 s10, s10, 0x1100
	s_subb_u32 s11, s11, 0
	global_atomic_add v183, v2, s[10:11]
	global_atomic_add v183, v2, s[10:11] offset:256
	global_atomic_add v183, v2, s[10:11] offset:512
	global_atomic_add v183, v2, s[10:11] offset:768
	global_atomic_add v183, v2, s[10:11] offset:1024
	global_atomic_add v183, v2, s[10:11] offset:1280
	global_atomic_add v183, v2, s[10:11] offset:1536
	global_atomic_add v183, v2, s[10:11] offset:1792
	global_atomic_add v183, v2, s[10:11] offset:2048
	global_atomic_add v183, v2, s[10:11] offset:2304
	global_atomic_add v183, v2, s[10:11] offset:2560
	global_atomic_add v183, v2, s[10:11] offset:2816
	global_atomic_add v183, v2, s[10:11] offset:3072
	global_atomic_add v183, v2, s[10:11] offset:3328
	global_atomic_add v183, v2, s[10:11] offset:3584
	global_atomic_add v183, v2, s[10:11] offset:3840
.Lxg_skip:
.LBB0_664:
	s_or_b64 exec, exec, s[6:7]
	s_mov_b64 s[6:7], exec
	v_mbcnt_lo_u32_b32 v0, s6, 0
	v_mbcnt_hi_u32_b32 v0, s7, v0
	v_cmp_eq_u32_e32 vcc, 0, v0
	s_waitcnt vmcnt(0)
	buffer_inv sc1
	s_and_saveexec_b64 s[8:9], vcc
	s_cbranch_execz .LBB0_666
	s_bcnt1_i32_b64 s6, s[6:7]
	v_mov_b32_e32 v0, s6
	v_readlane_b32 s6, v253, 40
	v_readlane_b32 s7, v253, 41
	s_nop 4
